# v67 + 7.12 branch-chain trim: two canonicalising self-max ops after the cross-half permlane removed in each attention loop (row-max -> rescale-branch chain 2 VALU shorter)
# speedup vs baseline: 1.0178x; 1.0178x over previous
; template <int DQK, int KROW, bool BIAS, bool MAPS2>
; DI void attn_core(const int t, const u16* __restrict__ Q, int ldq, const u16* __restrict__ Kp, int ldk, const u16* __restrict__ Vt, int q0,
;                   char* lds, const float* lut, float b31, f32x16 (&o)[4], float& l_out) {
;     ...
;       float mx = s[0][0];
; #pragma unroll
;       for (int k2 = 0; k2 < 2; ++k2)
; #pragma unroll
;         for (int i = 0; i < 16; ++i) mx = fmaxf(mx, s[k2][i]);
;       mx = xhalf_max(mx);
;       if (__builtin_amdgcn_ballot_w64(kt == 0 || mx > RESCALE_THR)) {
;         const float delta = (kt == 0) ? mx : fmaxf(mx, 0.f);
;         const float alpha = __builtin_amdgcn_exp2f(-delta);
;         m_run += delta;
;         l_run *= alpha;
; #pragma unroll
;         for (int dt = 0; dt < 4; ++dt)
; #pragma unroll
;           for (int i = 0; i < 16; ++i) o[dt][i] *= alpha;
; #pragma unroll
;         for (int k2 = 0; k2 < 2; ++k2)
; #pragma unroll
;           for (int i = 0; i < 16; ++i) s[k2][i] -= delta;
;       }
.LBB0_238:
	s_or_b64 exec, exec, s[0:1]
	s_nop 4
	s_nop 0
	v_max_f32_e32 v0, v97, v97
	v_max_f32_e32 v2, v96, v96
	v_max_f32_e32 v0, v2, v0
	v_max3_f32 v0, v0, v98, v99
	v_max3_f32 v0, v0, v100, v101
	v_max3_f32 v0, v0, v102, v103
	v_max3_f32 v0, v0, v104, v105
	v_max3_f32 v0, v0, v106, v107
	v_max3_f32 v0, v0, v108, v109
	v_max3_f32 v0, v0, v110, v111
	v_max3_f32 v0, v0, v80, v81
	v_max3_f32 v0, v0, v82, v83
	v_max3_f32 v0, v0, v84, v85
	v_max3_f32 v0, v0, v86, v87
	v_max3_f32 v0, v0, v88, v89
	v_max3_f32 v0, v0, v90, v91
	v_max3_f32 v0, v0, v92, v93
	v_max3_f32 v0, v0, v94, v95
	v_mov_b32_e32 v2, v0
	s_nop 1
	v_permlane32_swap_b32_e32 v0, v2
	v_max_f32_e32 v0, v0, v2
	s_cmp_eq_u32 s96, 0
	s_cselect_b64 s[0:1], -1, 0
	v_cmp_lt_f32_e32 vcc, s6, v0
	s_or_b64 vcc, s[0:1], vcc
	s_cbranch_vccz .LBB0_242
	v_max_f32_e32 v2, v0, v0
	v_max_f32_e32 v2, 0, v2
	v_cndmask_b32_e64 v0, v2, v0, s[0:1]
	v_exp_f32_e64 v2, -v0
	v_add_f32_e32 v161, v161, v0
	v_pk_add_f32 v[96:97], v[96:97], v[0:1] op_sel_hi:[1,0] neg_lo:[0,1] neg_hi:[0,1]
	v_pk_add_f32 v[98:99], v[98:99], v[0:1] op_sel_hi:[1,0] neg_lo:[0,1] neg_hi:[0,1]
	v_pk_mul_f32 v[78:79], v[78:79], v[2:3] op_sel_hi:[1,0]
	v_pk_mul_f32 v[76:77], v[76:77], v[2:3] op_sel_hi:[1,0]
	v_pk_mul_f32 v[74:75], v[74:75], v[2:3] op_sel_hi:[1,0]
	v_pk_mul_f32 v[72:73], v[72:73], v[2:3] op_sel_hi:[1,0]
	v_pk_mul_f32 v[70:71], v[70:71], v[2:3] op_sel_hi:[1,0]
	v_pk_mul_f32 v[68:69], v[68:69], v[2:3] op_sel_hi:[1,0]
	v_pk_mul_f32 v[66:67], v[66:67], v[2:3] op_sel_hi:[1,0]
	v_pk_mul_f32 v[64:65], v[64:65], v[2:3] op_sel_hi:[1,0]
	v_pk_mul_f32 v[62:63], v[62:63], v[2:3] op_sel_hi:[1,0]
	v_pk_mul_f32 v[60:61], v[60:61], v[2:3] op_sel_hi:[1,0]
	v_pk_mul_f32 v[58:59], v[58:59], v[2:3] op_sel_hi:[1,0]
	v_pk_mul_f32 v[56:57], v[56:57], v[2:3] op_sel_hi:[1,0]
	v_pk_mul_f32 v[54:55], v[54:55], v[2:3] op_sel_hi:[1,0]
	v_pk_mul_f32 v[52:53], v[52:53], v[2:3] op_sel_hi:[1,0]
	v_pk_mul_f32 v[50:51], v[50:51], v[2:3] op_sel_hi:[1,0]
	v_pk_mul_f32 v[48:49], v[48:49], v[2:3] op_sel_hi:[1,0]
	v_pk_mul_f32 v[46:47], v[46:47], v[2:3] op_sel_hi:[1,0]
	v_pk_mul_f32 v[44:45], v[44:45], v[2:3] op_sel_hi:[1,0]
	v_pk_mul_f32 v[42:43], v[42:43], v[2:3] op_sel_hi:[1,0]
	v_pk_mul_f32 v[40:41], v[40:41], v[2:3] op_sel_hi:[1,0]
	v_pk_mul_f32 v[38:39], v[38:39], v[2:3] op_sel_hi:[1,0]
	v_pk_mul_f32 v[36:37], v[36:37], v[2:3] op_sel_hi:[1,0]
	v_pk_mul_f32 v[34:35], v[34:35], v[2:3] op_sel_hi:[1,0]
	v_pk_mul_f32 v[32:33], v[32:33], v[2:3] op_sel_hi:[1,0]
	v_pk_mul_f32 v[30:31], v[30:31], v[2:3] op_sel_hi:[1,0]
	v_pk_mul_f32 v[28:29], v[28:29], v[2:3] op_sel_hi:[1,0]
	v_pk_mul_f32 v[26:27], v[26:27], v[2:3] op_sel_hi:[1,0]
	v_pk_mul_f32 v[24:25], v[24:25], v[2:3] op_sel_hi:[1,0]
	v_pk_mul_f32 v[22:23], v[22:23], v[2:3] op_sel_hi:[1,0]
	v_pk_mul_f32 v[20:21], v[20:21], v[2:3] op_sel_hi:[1,0]
	v_pk_mul_f32 v[18:19], v[18:19], v[2:3] op_sel_hi:[1,0]
	v_pk_mul_f32 v[16:17], v[16:17], v[2:3] op_sel_hi:[1,0]
	v_pk_add_f32 v[100:101], v[100:101], v[0:1] op_sel_hi:[1,0] neg_lo:[0,1] neg_hi:[0,1]
	v_pk_add_f32 v[102:103], v[102:103], v[0:1] op_sel_hi:[1,0] neg_lo:[0,1] neg_hi:[0,1]
	v_pk_add_f32 v[104:105], v[104:105], v[0:1] op_sel_hi:[1,0] neg_lo:[0,1] neg_hi:[0,1]
	v_pk_add_f32 v[106:107], v[106:107], v[0:1] op_sel_hi:[1,0] neg_lo:[0,1] neg_hi:[0,1]
	v_pk_add_f32 v[108:109], v[108:109], v[0:1] op_sel_hi:[1,0] neg_lo:[0,1] neg_hi:[0,1]
	v_pk_add_f32 v[110:111], v[110:111], v[0:1] op_sel_hi:[1,0] neg_lo:[0,1] neg_hi:[0,1]
	v_pk_add_f32 v[80:81], v[80:81], v[0:1] op_sel_hi:[1,0] neg_lo:[0,1] neg_hi:[0,1]
	v_pk_add_f32 v[82:83], v[82:83], v[0:1] op_sel_hi:[1,0] neg_lo:[0,1] neg_hi:[0,1]
	v_pk_add_f32 v[84:85], v[84:85], v[0:1] op_sel_hi:[1,0] neg_lo:[0,1] neg_hi:[0,1]
	v_pk_add_f32 v[86:87], v[86:87], v[0:1] op_sel_hi:[1,0] neg_lo:[0,1] neg_hi:[0,1]
	v_pk_add_f32 v[88:89], v[88:89], v[0:1] op_sel_hi:[1,0] neg_lo:[0,1] neg_hi:[0,1]
	v_pk_add_f32 v[90:91], v[90:91], v[0:1] op_sel_hi:[1,0] neg_lo:[0,1] neg_hi:[0,1]
	v_pk_add_f32 v[92:93], v[92:93], v[0:1] op_sel_hi:[1,0] neg_lo:[0,1] neg_hi:[0,1]
	v_pk_add_f32 v[94:95], v[94:95], v[0:1] op_sel_hi:[1,0] neg_lo:[0,1] neg_hi:[0,1]
	v_mul_f32_e32 v151, v151, v2

; template <int DQK, int KROW, bool BIAS, bool MAPS2>
; DI void attn_core(const int t, const u16* __restrict__ Q, int ldq, const u16* __restrict__ Kp, int ldk, const u16* __restrict__ Vt, int q0,
;                   char* lds, const float* lut, float b31, f32x16 (&o)[4], float& l_out) {
;     ...
;       float mx = s[0][0];
; #pragma unroll
;       for (int k2 = 0; k2 < 2; ++k2)
; #pragma unroll
;         for (int i = 0; i < 16; ++i) mx = fmaxf(mx, s[k2][i]);
;       mx = xhalf_max(mx);
;       if (__builtin_amdgcn_ballot_w64(kt == 0 || mx > RESCALE_THR)) {
;         const float delta = (kt == 0) ? mx : fmaxf(mx, 0.f);
;         const float alpha = __builtin_amdgcn_exp2f(-delta);
;         m_run += delta;
;         l_run *= alpha;
; #pragma unroll
;         for (int dt = 0; dt < 4; ++dt)
; #pragma unroll
;           for (int i = 0; i < 16; ++i) o[dt][i] *= alpha;
; #pragma unroll
;         for (int k2 = 0; k2 < 2; ++k2)
; #pragma unroll
;           for (int i = 0; i < 16; ++i) s[k2][i] -= delta;
;       }
.LBB0_259:
	s_or_b64 exec, exec, s[0:1]
	s_nop 3
	v_max_f32_e32 v181, v83, v83
	v_max_f32_e32 v182, v82, v82
	v_max_f32_e32 v181, v182, v181
	v_max3_f32 v181, v181, v84, v85
	v_max3_f32 v181, v181, v86, v87
	v_max3_f32 v181, v181, v88, v89
	v_max3_f32 v181, v181, v90, v91
	v_max3_f32 v181, v181, v92, v93
	v_max3_f32 v181, v181, v94, v95
	v_max3_f32 v181, v181, v96, v97
	v_max3_f32 v181, v181, v66, v67
	v_max3_f32 v181, v181, v68, v69
	v_max3_f32 v181, v181, v70, v71
	v_max3_f32 v181, v181, v72, v73
	v_max3_f32 v181, v181, v74, v75
	v_max3_f32 v181, v181, v76, v77
	v_max3_f32 v181, v181, v78, v79
	v_max3_f32 v181, v181, v80, v81
	v_mov_b32_e32 v182, v181
	s_nop 1
	v_permlane32_swap_b32_e32 v181, v182
	v_max_f32_e32 v181, v181, v182
	s_cmp_eq_u32 s93, 0
	s_cselect_b64 s[0:1], -1, 0
	v_cmp_lt_f32_e32 vcc, s6, v181
	s_or_b64 vcc, s[0:1], vcc
	s_cbranch_vccz .LBB0_261
	v_max_f32_e32 v182, v181, v181
	v_max_f32_e32 v182, 0, v182
	v_cndmask_b32_e64 v182, v182, v181, s[0:1]
	v_exp_f32_e64 v184, -v182
	v_add_f32_e32 v180, v180, v182
	v_pk_add_f32 v[82:83], v[82:83], v[182:183] op_sel_hi:[1,0] neg_lo:[0,1] neg_hi:[0,1]
	v_pk_add_f32 v[84:85], v[84:85], v[182:183] op_sel_hi:[1,0] neg_lo:[0,1] neg_hi:[0,1]
	v_pk_mul_f32 v[64:65], v[64:65], v[184:185] op_sel_hi:[1,0]
	v_pk_mul_f32 v[62:63], v[62:63], v[184:185] op_sel_hi:[1,0]
	v_pk_mul_f32 v[60:61], v[60:61], v[184:185] op_sel_hi:[1,0]
	v_pk_mul_f32 v[58:59], v[58:59], v[184:185] op_sel_hi:[1,0]
	v_pk_mul_f32 v[56:57], v[56:57], v[184:185] op_sel_hi:[1,0]
	v_pk_mul_f32 v[54:55], v[54:55], v[184:185] op_sel_hi:[1,0]
	v_pk_mul_f32 v[52:53], v[52:53], v[184:185] op_sel_hi:[1,0]
	v_pk_mul_f32 v[50:51], v[50:51], v[184:185] op_sel_hi:[1,0]
	v_pk_mul_f32 v[48:49], v[48:49], v[184:185] op_sel_hi:[1,0]
	v_pk_mul_f32 v[46:47], v[46:47], v[184:185] op_sel_hi:[1,0]
	v_pk_mul_f32 v[44:45], v[44:45], v[184:185] op_sel_hi:[1,0]
	v_pk_mul_f32 v[42:43], v[42:43], v[184:185] op_sel_hi:[1,0]
	v_pk_mul_f32 v[40:41], v[40:41], v[184:185] op_sel_hi:[1,0]
	v_pk_mul_f32 v[38:39], v[38:39], v[184:185] op_sel_hi:[1,0]
	v_pk_mul_f32 v[36:37], v[36:37], v[184:185] op_sel_hi:[1,0]
	v_pk_mul_f32 v[34:35], v[34:35], v[184:185] op_sel_hi:[1,0]
	v_pk_mul_f32 v[32:33], v[32:33], v[184:185] op_sel_hi:[1,0]
	v_pk_mul_f32 v[30:31], v[30:31], v[184:185] op_sel_hi:[1,0]
	v_pk_mul_f32 v[28:29], v[28:29], v[184:185] op_sel_hi:[1,0]
	v_pk_mul_f32 v[26:27], v[26:27], v[184:185] op_sel_hi:[1,0]
	v_pk_mul_f32 v[24:25], v[24:25], v[184:185] op_sel_hi:[1,0]
	v_pk_mul_f32 v[22:23], v[22:23], v[184:185] op_sel_hi:[1,0]
	v_pk_mul_f32 v[20:21], v[20:21], v[184:185] op_sel_hi:[1,0]
	v_pk_mul_f32 v[18:19], v[18:19], v[184:185] op_sel_hi:[1,0]
	v_pk_mul_f32 v[16:17], v[16:17], v[184:185] op_sel_hi:[1,0]
	v_pk_mul_f32 v[14:15], v[14:15], v[184:185] op_sel_hi:[1,0]
	v_pk_mul_f32 v[12:13], v[12:13], v[184:185] op_sel_hi:[1,0]
	v_pk_mul_f32 v[10:11], v[10:11], v[184:185] op_sel_hi:[1,0]
	v_pk_mul_f32 v[8:9], v[8:9], v[184:185] op_sel_hi:[1,0]
	v_pk_mul_f32 v[6:7], v[6:7], v[184:185] op_sel_hi:[1,0]
	v_pk_mul_f32 v[4:5], v[4:5], v[184:185] op_sel_hi:[1,0]
	v_pk_mul_f32 v[2:3], v[2:3], v[184:185] op_sel_hi:[1,0]
	v_pk_add_f32 v[86:87], v[86:87], v[182:183] op_sel_hi:[1,0] neg_lo:[0,1] neg_hi:[0,1]
	v_pk_add_f32 v[88:89], v[88:89], v[182:183] op_sel_hi:[1,0] neg_lo:[0,1] neg_hi:[0,1]
	v_pk_add_f32 v[90:91], v[90:91], v[182:183] op_sel_hi:[1,0] neg_lo:[0,1] neg_hi:[0,1]
	v_pk_add_f32 v[92:93], v[92:93], v[182:183] op_sel_hi:[1,0] neg_lo:[0,1] neg_hi:[0,1]
	v_pk_add_f32 v[94:95], v[94:95], v[182:183] op_sel_hi:[1,0] neg_lo:[0,1] neg_hi:[0,1]
	v_pk_add_f32 v[96:97], v[96:97], v[182:183] op_sel_hi:[1,0] neg_lo:[0,1] neg_hi:[0,1]
	v_pk_add_f32 v[66:67], v[66:67], v[182:183] op_sel_hi:[1,0] neg_lo:[0,1] neg_hi:[0,1]
	v_pk_add_f32 v[68:69], v[68:69], v[182:183] op_sel_hi:[1,0] neg_lo:[0,1] neg_hi:[0,1]
	v_pk_add_f32 v[70:71], v[70:71], v[182:183] op_sel_hi:[1,0] neg_lo:[0,1] neg_hi:[0,1]
	v_pk_add_f32 v[72:73], v[72:73], v[182:183] op_sel_hi:[1,0] neg_lo:[0,1] neg_hi:[0,1]
	v_pk_add_f32 v[74:75], v[74:75], v[182:183] op_sel_hi:[1,0] neg_lo:[0,1] neg_hi:[0,1]
	v_pk_add_f32 v[76:77], v[76:77], v[182:183] op_sel_hi:[1,0] neg_lo:[0,1] neg_hi:[0,1]
	v_pk_add_f32 v[78:79], v[78:79], v[182:183] op_sel_hi:[1,0] neg_lo:[0,1] neg_hi:[0,1]
	v_pk_add_f32 v[80:81], v[80:81], v[182:183] op_sel_hi:[1,0] neg_lo:[0,1] neg_hi:[0,1]
	v_mul_f32_e32 v0, v0, v184

; template <int DQK, int KROW, bool BIAS, bool MAPS2>
; DI void attn_core(const int t, const u16* __restrict__ Q, int ldq, const u16* __restrict__ Kp, int ldk, const u16* __restrict__ Vt, int q0,
;                   char* lds, const float* lut, float b31, f32x16 (&o)[4], float& l_out) {
;     ...
;       float mx = s[0][0];
; #pragma unroll
;       for (int k2 = 0; k2 < 2; ++k2)
; #pragma unroll
;         for (int i = 0; i < 16; ++i) mx = fmaxf(mx, s[k2][i]);
;       mx = xhalf_max(mx);
;       if (__builtin_amdgcn_ballot_w64(kt == 0 || mx > RESCALE_THR)) {
;         const float delta = (kt == 0) ? mx : fmaxf(mx, 0.f);
;         const float alpha = __builtin_amdgcn_exp2f(-delta);
;         m_run += delta;
;         l_run *= alpha;
; #pragma unroll
;         for (int dt = 0; dt < 4; ++dt)
; #pragma unroll
;           for (int i = 0; i < 16; ++i) o[dt][i] *= alpha;
; #pragma unroll
;         for (int k2 = 0; k2 < 2; ++k2)
; #pragma unroll
;           for (int i = 0; i < 16; ++i) s[k2][i] -= delta;
;       }
.LBB0_273:
	s_or_b64 exec, exec, s[0:1]
	s_nop 3
	v_max_f32_e32 v181, v83, v83
	v_max_f32_e32 v182, v82, v82
	v_max_f32_e32 v181, v182, v181
	v_max3_f32 v181, v181, v84, v85
	v_max3_f32 v181, v181, v86, v87
	v_max3_f32 v181, v181, v88, v89
	v_max3_f32 v181, v181, v90, v91
	v_max3_f32 v181, v181, v92, v93
	v_max3_f32 v181, v181, v94, v95
	v_max3_f32 v181, v181, v96, v97
	v_max3_f32 v181, v181, v66, v67
	v_max3_f32 v181, v181, v68, v69
	v_max3_f32 v181, v181, v70, v71
	v_max3_f32 v181, v181, v72, v73
	v_max3_f32 v181, v181, v74, v75
	v_max3_f32 v181, v181, v76, v77
	v_max3_f32 v181, v181, v78, v79
	v_max3_f32 v181, v181, v80, v81
	v_mov_b32_e32 v182, v181
	s_nop 1
	v_permlane32_swap_b32_e32 v181, v182
	v_max_f32_e32 v181, v181, v182
	s_cmp_eq_u32 s63, 0
	s_cselect_b64 s[0:1], -1, 0
	v_cmp_lt_f32_e32 vcc, s6, v181
	s_or_b64 vcc, s[0:1], vcc
	s_cbranch_vccz .LBB0_275
	v_max_f32_e32 v182, v181, v181
	v_max_f32_e32 v182, 0, v182
	v_cndmask_b32_e64 v182, v182, v181, s[0:1]
	v_exp_f32_e64 v184, -v182
	v_add_f32_e32 v180, v180, v182
	v_pk_add_f32 v[82:83], v[82:83], v[182:183] op_sel_hi:[1,0] neg_lo:[0,1] neg_hi:[0,1]
	v_pk_add_f32 v[84:85], v[84:85], v[182:183] op_sel_hi:[1,0] neg_lo:[0,1] neg_hi:[0,1]
	v_pk_mul_f32 v[64:65], v[64:65], v[184:185] op_sel_hi:[1,0]
	v_pk_mul_f32 v[62:63], v[62:63], v[184:185] op_sel_hi:[1,0]
	v_pk_mul_f32 v[60:61], v[60:61], v[184:185] op_sel_hi:[1,0]
	v_pk_mul_f32 v[58:59], v[58:59], v[184:185] op_sel_hi:[1,0]
	v_pk_mul_f32 v[56:57], v[56:57], v[184:185] op_sel_hi:[1,0]
	v_pk_mul_f32 v[54:55], v[54:55], v[184:185] op_sel_hi:[1,0]
	v_pk_mul_f32 v[52:53], v[52:53], v[184:185] op_sel_hi:[1,0]
	v_pk_mul_f32 v[50:51], v[50:51], v[184:185] op_sel_hi:[1,0]
	v_pk_mul_f32 v[48:49], v[48:49], v[184:185] op_sel_hi:[1,0]
	v_pk_mul_f32 v[46:47], v[46:47], v[184:185] op_sel_hi:[1,0]
	v_pk_mul_f32 v[44:45], v[44:45], v[184:185] op_sel_hi:[1,0]
	v_pk_mul_f32 v[42:43], v[42:43], v[184:185] op_sel_hi:[1,0]
	v_pk_mul_f32 v[40:41], v[40:41], v[184:185] op_sel_hi:[1,0]
	v_pk_mul_f32 v[38:39], v[38:39], v[184:185] op_sel_hi:[1,0]
	v_pk_mul_f32 v[36:37], v[36:37], v[184:185] op_sel_hi:[1,0]
	v_pk_mul_f32 v[34:35], v[34:35], v[184:185] op_sel_hi:[1,0]
	v_pk_mul_f32 v[32:33], v[32:33], v[184:185] op_sel_hi:[1,0]
	v_pk_mul_f32 v[30:31], v[30:31], v[184:185] op_sel_hi:[1,0]
	v_pk_mul_f32 v[28:29], v[28:29], v[184:185] op_sel_hi:[1,0]
	v_pk_mul_f32 v[26:27], v[26:27], v[184:185] op_sel_hi:[1,0]
	v_pk_mul_f32 v[24:25], v[24:25], v[184:185] op_sel_hi:[1,0]
	v_pk_mul_f32 v[22:23], v[22:23], v[184:185] op_sel_hi:[1,0]
	v_pk_mul_f32 v[20:21], v[20:21], v[184:185] op_sel_hi:[1,0]
	v_pk_mul_f32 v[18:19], v[18:19], v[184:185] op_sel_hi:[1,0]
	v_pk_mul_f32 v[16:17], v[16:17], v[184:185] op_sel_hi:[1,0]
	v_pk_mul_f32 v[14:15], v[14:15], v[184:185] op_sel_hi:[1,0]
	v_pk_mul_f32 v[12:13], v[12:13], v[184:185] op_sel_hi:[1,0]
	v_pk_mul_f32 v[10:11], v[10:11], v[184:185] op_sel_hi:[1,0]
	v_pk_mul_f32 v[8:9], v[8:9], v[184:185] op_sel_hi:[1,0]
	v_pk_mul_f32 v[6:7], v[6:7], v[184:185] op_sel_hi:[1,0]
	v_pk_mul_f32 v[4:5], v[4:5], v[184:185] op_sel_hi:[1,0]
	v_pk_mul_f32 v[2:3], v[2:3], v[184:185] op_sel_hi:[1,0]
	v_pk_add_f32 v[86:87], v[86:87], v[182:183] op_sel_hi:[1,0] neg_lo:[0,1] neg_hi:[0,1]
	v_pk_add_f32 v[88:89], v[88:89], v[182:183] op_sel_hi:[1,0] neg_lo:[0,1] neg_hi:[0,1]
	v_pk_add_f32 v[90:91], v[90:91], v[182:183] op_sel_hi:[1,0] neg_lo:[0,1] neg_hi:[0,1]
	v_pk_add_f32 v[92:93], v[92:93], v[182:183] op_sel_hi:[1,0] neg_lo:[0,1] neg_hi:[0,1]
	v_pk_add_f32 v[94:95], v[94:95], v[182:183] op_sel_hi:[1,0] neg_lo:[0,1] neg_hi:[0,1]
	v_pk_add_f32 v[96:97], v[96:97], v[182:183] op_sel_hi:[1,0] neg_lo:[0,1] neg_hi:[0,1]
	v_pk_add_f32 v[66:67], v[66:67], v[182:183] op_sel_hi:[1,0] neg_lo:[0,1] neg_hi:[0,1]
	v_pk_add_f32 v[68:69], v[68:69], v[182:183] op_sel_hi:[1,0] neg_lo:[0,1] neg_hi:[0,1]
	v_pk_add_f32 v[70:71], v[70:71], v[182:183] op_sel_hi:[1,0] neg_lo:[0,1] neg_hi:[0,1]
	v_pk_add_f32 v[72:73], v[72:73], v[182:183] op_sel_hi:[1,0] neg_lo:[0,1] neg_hi:[0,1]
	v_pk_add_f32 v[74:75], v[74:75], v[182:183] op_sel_hi:[1,0] neg_lo:[0,1] neg_hi:[0,1]
	v_pk_add_f32 v[76:77], v[76:77], v[182:183] op_sel_hi:[1,0] neg_lo:[0,1] neg_hi:[0,1]
	v_pk_add_f32 v[78:79], v[78:79], v[182:183] op_sel_hi:[1,0] neg_lo:[0,1] neg_hi:[0,1]
	v_pk_add_f32 v[80:81], v[80:81], v[182:183] op_sel_hi:[1,0] neg_lo:[0,1] neg_hi:[0,1]
	v_mul_f32_e32 v0, v0, v184
